# v14 plus nt cache policy on the once-read KVC loads and once-written ST stores of GLA pass 2 (P3)
# baseline (speedup 1.0000x reference)
.LBB0_677:
	v_lshl_add_u64 v[24:25], s[38:39], 0, v[12:13]
	v_bfe_u32 v20, v8, 16, 1
	v_bfe_u32 v21, v9, 16, 1
	v_add3_u32 v27, v8, v20, s20
	v_add_co_u32_e64 v20, s[6:7], s21, v24
	v_bfe_u32 v19, v11, 16, 1
	v_add_co_u32_e32 v18, vcc, 0x3d600000, v24
	v_add3_u32 v33, v9, v21, s20
	v_addc_co_u32_e64 v21, s[6:7], 0, v25, s[6:7]
	v_lshl_add_u64 v[16:17], s[38:39], 0, v[6:7]
	v_bfe_u32 v0, v10, 16, 1
	v_add3_u32 v32, v11, v19, s20
	v_add_co_u32_e64 v22, s[6:7], s22, v24
	v_addc_co_u32_e32 v19, vcc, 0, v25, vcc
	v_add3_u32 v0, v10, v0, s20
	v_addc_co_u32_e64 v23, s[6:7], 0, v25, s[6:7]
	v_add_co_u32_e32 v26, vcc, 0x41700000, v16
	v_lshrrev_b32_e32 v0, 16, v0
	global_load_dwordx2 v[28:29], v[22:23], off nt
	global_load_dwordx2 v[30:31], v[18:19], off nt
	v_lshrrev_b32_e32 v16, 16, v27
	v_addc_co_u32_e32 v27, vcc, 0, v17, vcc
	v_and_or_b32 v22, v32, s18, v0
	v_and_or_b32 v23, v33, s18, v16
	global_load_dwordx4 v[16:19], v[26:27], off
	s_add_i32 s25, s25, -2
	global_store_dwordx2 v[20:21], v[22:23], off nt
	global_load_dwordx4 v[20:23], v[26:27], off offset:256
	v_add_co_u32_e32 v24, vcc, s23, v24
	v_lshl_add_u64 v[6:7], v[6:7], 0, s[14:15]
	v_lshl_add_u64 v[12:13], v[12:13], 0, s[16:17]
	v_addc_co_u32_e32 v25, vcc, 0, v25, vcc
	s_cmp_eq_u32 s25, 0
	s_waitcnt vmcnt(4)
	v_lshlrev_b32_e32 v26, 16, v28
	s_waitcnt vmcnt(3)
	v_lshlrev_b32_e32 v32, 16, v30
	v_and_b32_e32 v33, 0xffff0000, v30
	v_lshlrev_b32_e32 v30, 16, v31
	v_and_b32_e32 v31, 0xffff0000, v31
	v_and_b32_e32 v27, 0xffff0000, v28
	v_lshlrev_b32_e32 v28, 16, v29
	s_waitcnt vmcnt(2)
	v_pk_fma_f32 v[18:19], v[8:9], v[18:19], v[30:31]
	v_pk_fma_f32 v[16:17], v[10:11], v[16:17], v[32:33]
	v_bfe_u32 v31, v18, 16, 1
	v_bfe_u32 v0, v16, 16, 1
	v_bfe_u32 v30, v17, 16, 1
	v_and_b32_e32 v29, 0xffff0000, v29
	v_bfe_u32 v32, v19, 16, 1
	s_waitcnt vmcnt(0)
	v_pk_fma_f32 v[10:11], v[16:17], v[20:21], v[26:27]
	v_add3_u32 v0, v16, v0, s20
	v_add3_u32 v16, v17, v30, s20
	v_add3_u32 v17, v18, v31, s20
	v_pk_fma_f32 v[8:9], v[18:19], v[22:23], v[28:29]
	v_add3_u32 v18, v19, v32, s20
	v_lshrrev_b32_e32 v0, 16, v0
	v_lshrrev_b32_e32 v17, 16, v17
	v_and_or_b32 v16, v16, s18, v0
	v_and_or_b32 v17, v18, s18, v17
	global_store_dwordx2 v[24:25], v[16:17], off nt
	s_cbranch_scc0 .LBB0_677
	v_lshlrev_b64 v[2:3], 15, v[2:3]
	v_lshl_add_u64 v[2:3], s[10:11], 0, v[2:3]
	v_lshlrev_b32_e32 v0, 9, v4
	v_add_u32_e32 v5, s3, v5
	v_lshl_add_u64 v[2:3], v[2:3], 0, v[0:1]
	v_lshlrev_b32_e32 v0, 2, v15
	v_cmp_lt_i32_e32 vcc, s24, v5
	v_lshl_add_u64 v[2:3], v[2:3], 0, v[0:1]
	s_or_b64 s[12:13], vcc, s[12:13]
	v_add_u32_e32 v14, s4, v14
	global_store_dword v[2:3], v10, off
	global_store_dword v[2:3], v11, off offset:512
	global_store_dword v[2:3], v8, off offset:1024
	global_store_dword v[2:3], v9, off offset:1536
	s_andn2_b64 exec, exec, s[12:13]
	s_cbranch_execnz .LBB0_676
